# P9 gate-up epilogue: 8 rsq loads hoisted to epilogue start, counted vmcnt(7) instead of vmcnt(0) after each store
# speedup vs baseline: 1.0017x; 1.0017x over previous
; __device__ __forceinline__ u32x4 pack8(f32x4 v0, f32x4 v1) { u32x4 w; w.x = cvt_pk_bf16(v0[0], v0[1]); w.y = cvt_pk_bf16(v0[2], v0[3]); w.z = cvt_pk_bf16(v1[0], v1[1]); w.w = cvt_pk_bf16(v1[2], v1[3]); return w; }
;     __device__ __forceinline__ void operator()(EPI_ARGS) const {
;         const int col0 = u.pn * 128 + wc * 32 + 8 * fq;
; #pragma unroll
;         for (int ai = 0; ai < 2; ++ai)
; #pragma unroll
;             for (int m = 0; m < 4; ++m) { const int row = EPI_ROW(ai, m); const float rs = __builtin_amdgcn_rsqf(rsq[row] * (1.f / DM) + RMS_EPS); f32x4 v0, v1;
;                 const float c1 = -1.4426950408889634f * rs, rs2 = rs * rs;
;                 { const f32x4 g = acc[ai][0][m][0], u = acc[ai][1][m][0]; f32x4 t = g * c1, r;
; #pragma unroll
;                   for (int e = 0; e < 4; ++e) t[e] = __builtin_amdgcn_exp2f(t[e]);
;                   t = t + 1.f;
; #pragma unroll
;                   for (int e = 0; e < 4; ++e) r[e] = __builtin_amdgcn_rcpf(t[e]);
;                   v0 = (g * u) * (r * rs2); }
;                 { const f32x4 g = acc[ai][0][m][1], u = acc[ai][1][m][1]; f32x4 t = g * c1, r;
; #pragma unroll
;                   for (int e = 0; e < 4; ++e) t[e] = __builtin_amdgcn_exp2f(t[e]);
;                   t = t + 1.f;
; #pragma unroll
;                   for (int e = 0; e < 4; ++e) r[e] = __builtin_amdgcn_rcpf(t[e]);
;                   v1 = (g * u) * (r * rs2); }
;                 *(u32x4*)(H + (size_t)row * DFF + col0) = pack8(v0, v1);
;                 if (m & 1) asm volatile("" ::: "memory"); }
;     }
.LBB0_899:
	v_lshl_add_u32 v132, s50, 8, v139
	v_ashrrev_i32_e32 v133, 31, v132
	v_lshl_add_u64 v[154:155], v[132:133], 2, s[8:9]
	global_load_dword v224, v[154:155], off
	global_load_dword v225, v[154:155], off offset:64
	global_load_dword v226, v[154:155], off offset:128
	global_load_dword v227, v[154:155], off offset:192
	global_load_dword v228, v[154:155], off offset:512
	global_load_dword v229, v[154:155], off offset:576
	global_load_dword v230, v[154:155], off offset:640
	global_load_dword v231, v[154:155], off offset:704
	v_pk_mul_f32 v[126:127], v[118:119], v[126:127]
	v_pk_mul_f32 v[124:125], v[116:117], v[124:125]
	v_pk_mul_f32 v[156:157], v[114:115], v[122:123]
	v_pk_mul_f32 v[158:159], v[112:113], v[120:121]
	v_lshl_or_b32 v154, s49, 7, v146
	v_mov_b64_e32 v[120:121], s[64:65]
	v_ashrrev_i32_e32 v155, 31, v154
	v_mad_i64_i32 v[166:167], s[26:27], v132, s46, v[120:121]
	v_or_b32_e32 v172, 16, v132
	v_lshlrev_b64 v[122:123], 1, v[154:155]
	v_ashrrev_i32_e32 v173, 31, v172
	v_lshl_add_u64 v[154:155], v[166:167], 0, v[122:123]
	v_lshl_add_u64 v[166:167], v[172:173], 2, s[8:9]
	v_pk_mul_f32 v[110:111], v[102:103], v[110:111]
	v_pk_mul_f32 v[108:109], v[100:101], v[108:109]
	v_pk_mul_f32 v[106:107], v[98:99], v[106:107]
	v_pk_mul_f32 v[104:105], v[96:97], v[104:105]
	v_pk_mul_f32 v[94:95], v[86:87], v[94:95]
	v_pk_mul_f32 v[92:93], v[84:85], v[92:93]
	v_pk_mul_f32 v[90:91], v[82:83], v[90:91]
	v_pk_mul_f32 v[88:89], v[80:81], v[88:89]
	v_pk_mul_f32 v[78:79], v[70:71], v[78:79]
	v_pk_mul_f32 v[76:77], v[68:69], v[76:77]
	v_pk_mul_f32 v[74:75], v[66:67], v[74:75]
	v_pk_mul_f32 v[72:73], v[64:65], v[72:73]
	v_pk_mul_f32 v[62:63], v[54:55], v[62:63]
	v_pk_mul_f32 v[60:61], v[52:53], v[60:61]
	v_pk_mul_f32 v[58:59], v[50:51], v[58:59]
	v_pk_mul_f32 v[56:57], v[48:49], v[56:57]
	v_pk_mul_f32 v[46:47], v[38:39], v[46:47]
	v_pk_mul_f32 v[44:45], v[36:37], v[44:45]
	v_pk_mul_f32 v[42:43], v[34:35], v[42:43]
	v_pk_mul_f32 v[40:41], v[32:33], v[40:41]
	v_pk_mul_f32 v[30:31], v[22:23], v[30:31]
	v_pk_mul_f32 v[28:29], v[20:21], v[28:29]
	v_pk_mul_f32 v[26:27], v[18:19], v[26:27]
	v_pk_mul_f32 v[24:25], v[16:17], v[24:25]
	v_pk_mul_f32 v[14:15], v[10:11], v[14:15]
	v_pk_mul_f32 v[12:13], v[8:9], v[12:13]
	v_pk_mul_f32 v[2:3], v[6:7], v[2:3]
	v_pk_mul_f32 v[0:1], v[4:5], v[0:1]
	s_andn2_b64 vcc, exec, s[4:5]
	s_mov_b64 s[4:5], -1
	s_waitcnt vmcnt(7)
	v_fmamk_f32 v133, v224, 0x3a000000, v152
	v_rsq_f32_e32 v133, v133
	s_nop 0
	v_mul_f32_e32 v174, 0xbfb8aa3b, v133
	v_pk_mul_f32 v[118:119], v[118:119], v[174:175] op_sel_hi:[1,0]
	v_pk_mul_f32 v[116:117], v[116:117], v[174:175] op_sel_hi:[1,0]
	v_pk_mul_f32 v[114:115], v[114:115], v[174:175] op_sel_hi:[1,0]
	v_pk_mul_f32 v[112:113], v[112:113], v[174:175] op_sel_hi:[1,0]
	v_exp_f32_e32 v116, v116
	v_exp_f32_e32 v117, v117
	v_exp_f32_e32 v118, v118
	v_exp_f32_e32 v119, v119
	v_exp_f32_e32 v112, v112
	v_exp_f32_e32 v113, v113
	v_exp_f32_e32 v114, v114
	v_exp_f32_e32 v115, v115
	v_add_f32_e32 v116, 1.0, v116
	v_add_f32_e32 v117, 1.0, v117
	v_add_f32_e32 v118, 1.0, v118
	v_add_f32_e32 v119, 1.0, v119
	v_mul_f32_e32 v176, v133, v133
	v_add_f32_e32 v133, 1.0, v112
	v_add_f32_e32 v153, 1.0, v113
	v_add_f32_e32 v161, 1.0, v114
	v_add_f32_e32 v163, 1.0, v115
	v_rcp_f32_e32 v112, v116
	v_rcp_f32_e32 v113, v117
	v_rcp_f32_e32 v114, v118
	v_rcp_f32_e32 v115, v119
	v_rcp_f32_e32 v116, v133
	v_rcp_f32_e32 v117, v153
	v_rcp_f32_e32 v118, v161
	v_rcp_f32_e32 v119, v163
	v_pk_mul_f32 v[112:113], v[176:177], v[112:113] op_sel_hi:[0,1]
	v_pk_mul_f32 v[114:115], v[176:177], v[114:115] op_sel_hi:[0,1]
	v_pk_mul_f32 v[116:117], v[176:177], v[116:117] op_sel_hi:[0,1]
	v_pk_mul_f32 v[118:119], v[176:177], v[118:119] op_sel_hi:[0,1]
	v_pk_mul_f32 v[114:115], v[126:127], v[114:115]
	v_pk_mul_f32 v[112:113], v[124:125], v[112:113]
	v_pk_mul_f32 v[118:119], v[156:157], v[118:119]
	v_pk_mul_f32 v[116:117], v[158:159], v[116:117]
	v_cvt_pk_bf16_f32 v112, v112, v113
	v_cvt_pk_bf16_f32 v113, v114, v115
	s_nop 0
	v_cvt_pk_bf16_f32 v114, v116, v117
	v_cvt_pk_bf16_f32 v115, v118, v119
	global_store_dwordx4 v[154:155], v[112:115], off
	s_nop 1
	s_nop 0
	v_or_b32_e32 v112, 32, v132
	v_mad_i64_i32 v[114:115], s[26:27], v172, s46, v[120:121]
	v_lshl_add_u64 v[114:115], v[114:115], 0, v[122:123]
	s_waitcnt vmcnt(7)
	v_fmamk_f32 v113, v225, 0x3a000000, v152
	v_rsq_f32_e32 v119, v113
	v_ashrrev_i32_e32 v113, 31, v112
	v_lshl_add_u64 v[116:117], v[112:113], 2, s[8:9]
	v_mul_f32_e32 v118, 0xbfb8aa3b, v119
	v_pk_mul_f32 v[102:103], v[102:103], v[118:119] op_sel_hi:[1,0]
	v_pk_mul_f32 v[100:101], v[100:101], v[118:119] op_sel_hi:[1,0]
	v_pk_mul_f32 v[98:99], v[98:99], v[118:119] op_sel_hi:[1,0]
	v_pk_mul_f32 v[96:97], v[96:97], v[118:119] op_sel_hi:[1,0]
	v_exp_f32_e32 v100, v100
	v_exp_f32_e32 v101, v101
	v_exp_f32_e32 v102, v102
	v_exp_f32_e32 v103, v103
	v_exp_f32_e32 v96, v96
	v_exp_f32_e32 v97, v97
	v_exp_f32_e32 v98, v98
	v_exp_f32_e32 v99, v99
	v_add_f32_e32 v100, 1.0, v100
	v_add_f32_e32 v101, 1.0, v101
	v_add_f32_e32 v102, 1.0, v102
	v_add_f32_e32 v103, 1.0, v103
	v_mul_f32_e32 v124, v119, v119
	v_add_f32_e32 v113, 1.0, v96
	v_add_f32_e32 v118, 1.0, v97
	v_add_f32_e32 v119, 1.0, v98
	v_add_f32_e32 v125, 1.0, v99
	v_rcp_f32_e32 v96, v100
	v_rcp_f32_e32 v97, v101
	v_rcp_f32_e32 v98, v102
	v_rcp_f32_e32 v99, v103
	v_rcp_f32_e32 v100, v113
	v_rcp_f32_e32 v101, v118
	v_rcp_f32_e32 v102, v119
	v_rcp_f32_e32 v103, v125
	v_pk_mul_f32 v[96:97], v[124:125], v[96:97] op_sel_hi:[0,1]
	v_pk_mul_f32 v[98:99], v[124:125], v[98:99] op_sel_hi:[0,1]
	v_pk_mul_f32 v[100:101], v[124:125], v[100:101] op_sel_hi:[0,1]
	v_pk_mul_f32 v[102:103], v[124:125], v[102:103] op_sel_hi:[0,1]
	v_pk_mul_f32 v[98:99], v[110:111], v[98:99]
	v_pk_mul_f32 v[96:97], v[108:109], v[96:97]
	v_pk_mul_f32 v[102:103], v[106:107], v[102:103]
	v_pk_mul_f32 v[100:101], v[104:105], v[100:101]
	v_cvt_pk_bf16_f32 v96, v96, v97
	v_cvt_pk_bf16_f32 v97, v98, v99
	s_nop 0
	v_cvt_pk_bf16_f32 v98, v100, v101
	v_cvt_pk_bf16_f32 v99, v102, v103
	global_store_dwordx4 v[114:115], v[96:99], off
	s_nop 1
	s_nop 0
	v_or_b32_e32 v96, 48, v132
	v_mad_i64_i32 v[98:99], s[26:27], v112, s46, v[120:121]
	v_lshl_add_u64 v[98:99], v[98:99], 0, v[122:123]
	s_waitcnt vmcnt(7)
; __device__ __forceinline__ u32x4 pack8(f32x4 v0, f32x4 v1) { u32x4 w; w.x = cvt_pk_bf16(v0[0], v0[1]); w.y = cvt_pk_bf16(v0[2], v0[3]); w.z = cvt_pk_bf16(v1[0], v1[1]); w.w = cvt_pk_bf16(v1[2], v1[3]); return w; }
;     __device__ __forceinline__ void operator()(EPI_ARGS) const {
;         const int col0 = u.pn * 128 + wc * 32 + 8 * fq;
; #pragma unroll
;         for (int ai = 0; ai < 2; ++ai)
; #pragma unroll
;             for (int m = 0; m < 4; ++m) { const int row = EPI_ROW(ai, m); const float rs = __builtin_amdgcn_rsqf(rsq[row] * (1.f / DM) + RMS_EPS); f32x4 v0, v1;
;                 const float c1 = -1.4426950408889634f * rs, rs2 = rs * rs;
;                 { const f32x4 g = acc[ai][0][m][0], u = acc[ai][1][m][0]; f32x4 t = g * c1, r;
; #pragma unroll
;                   for (int e = 0; e < 4; ++e) t[e] = __builtin_amdgcn_exp2f(t[e]);
;                   t = t + 1.f;
; #pragma unroll
;                   for (int e = 0; e < 4; ++e) r[e] = __builtin_amdgcn_rcpf(t[e]);
;                   v0 = (g * u) * (r * rs2); }
;                 { const f32x4 g = acc[ai][0][m][1], u = acc[ai][1][m][1]; f32x4 t = g * c1, r;
; #pragma unroll
;                   for (int e = 0; e < 4; ++e) t[e] = __builtin_amdgcn_exp2f(t[e]);
;                   t = t + 1.f;
; #pragma unroll
;                   for (int e = 0; e < 4; ++e) r[e] = __builtin_amdgcn_rcpf(t[e]);
;                   v1 = (g * u) * (r * rs2); }
;                 *(u32x4*)(H + (size_t)row * DFF + col0) = pack8(v0, v1);
;                 if (m & 1) asm volatile("" ::: "memory"); }
;     }
	v_fmamk_f32 v97, v226, 0x3a000000, v152
	v_rsq_f32_e32 v103, v97
	v_ashrrev_i32_e32 v97, 31, v96
	v_lshl_add_u64 v[100:101], v[96:97], 2, s[8:9]
	v_mul_f32_e32 v102, 0xbfb8aa3b, v103
	v_pk_mul_f32 v[86:87], v[86:87], v[102:103] op_sel_hi:[1,0]
	v_pk_mul_f32 v[84:85], v[84:85], v[102:103] op_sel_hi:[1,0]
	v_pk_mul_f32 v[82:83], v[82:83], v[102:103] op_sel_hi:[1,0]
	v_pk_mul_f32 v[80:81], v[80:81], v[102:103] op_sel_hi:[1,0]
	v_exp_f32_e32 v84, v84
	v_exp_f32_e32 v85, v85
	v_exp_f32_e32 v86, v86
	v_exp_f32_e32 v87, v87
	v_exp_f32_e32 v80, v80
	v_exp_f32_e32 v81, v81
	v_exp_f32_e32 v82, v82
	v_exp_f32_e32 v83, v83
	v_add_f32_e32 v84, 1.0, v84
	v_add_f32_e32 v85, 1.0, v85
	v_add_f32_e32 v86, 1.0, v86
	v_add_f32_e32 v87, 1.0, v87
	v_mul_f32_e32 v104, v103, v103
	v_add_f32_e32 v97, 1.0, v80
	v_add_f32_e32 v102, 1.0, v81
	v_add_f32_e32 v103, 1.0, v82
	v_add_f32_e32 v105, 1.0, v83
	v_rcp_f32_e32 v80, v84
	v_rcp_f32_e32 v81, v85
	v_rcp_f32_e32 v82, v86
	v_rcp_f32_e32 v83, v87
	v_rcp_f32_e32 v84, v97
	v_rcp_f32_e32 v85, v102
	v_rcp_f32_e32 v86, v103
	v_rcp_f32_e32 v87, v105
	v_pk_mul_f32 v[80:81], v[104:105], v[80:81] op_sel_hi:[0,1]
	v_pk_mul_f32 v[82:83], v[104:105], v[82:83] op_sel_hi:[0,1]
	v_pk_mul_f32 v[84:85], v[104:105], v[84:85] op_sel_hi:[0,1]
	v_pk_mul_f32 v[86:87], v[104:105], v[86:87] op_sel_hi:[0,1]
	v_pk_mul_f32 v[82:83], v[94:95], v[82:83]
	v_pk_mul_f32 v[80:81], v[92:93], v[80:81]
	v_pk_mul_f32 v[86:87], v[90:91], v[86:87]
	v_pk_mul_f32 v[84:85], v[88:89], v[84:85]
	v_cvt_pk_bf16_f32 v80, v80, v81
	v_cvt_pk_bf16_f32 v81, v82, v83
	s_nop 0
	v_cvt_pk_bf16_f32 v82, v84, v85
	v_cvt_pk_bf16_f32 v83, v86, v87
	global_store_dwordx4 v[98:99], v[80:83], off
	s_nop 1
	s_nop 0
	v_add_u32_e32 v80, 0x80, v132
	v_mad_i64_i32 v[82:83], s[26:27], v96, s46, v[120:121]
	v_lshl_add_u64 v[82:83], v[82:83], 0, v[122:123]
	s_waitcnt vmcnt(7)
	v_fmamk_f32 v81, v227, 0x3a000000, v152
	v_rsq_f32_e32 v87, v81
	v_ashrrev_i32_e32 v81, 31, v80
	v_lshl_add_u64 v[84:85], v[80:81], 2, s[8:9]
	v_mul_f32_e32 v86, 0xbfb8aa3b, v87
	v_pk_mul_f32 v[70:71], v[70:71], v[86:87] op_sel_hi:[1,0]
	v_pk_mul_f32 v[68:69], v[68:69], v[86:87] op_sel_hi:[1,0]
	v_pk_mul_f32 v[66:67], v[66:67], v[86:87] op_sel_hi:[1,0]
	v_pk_mul_f32 v[64:65], v[64:65], v[86:87] op_sel_hi:[1,0]
	v_exp_f32_e32 v68, v68
	v_exp_f32_e32 v69, v69
	v_exp_f32_e32 v70, v70
	v_exp_f32_e32 v71, v71
	v_exp_f32_e32 v64, v64
	v_exp_f32_e32 v65, v65
	v_exp_f32_e32 v66, v66
	v_exp_f32_e32 v67, v67
	v_add_f32_e32 v68, 1.0, v68
	v_add_f32_e32 v69, 1.0, v69
	v_add_f32_e32 v70, 1.0, v70
	v_add_f32_e32 v71, 1.0, v71
	v_mul_f32_e32 v88, v87, v87
	v_add_f32_e32 v81, 1.0, v64
	v_add_f32_e32 v86, 1.0, v65
	v_add_f32_e32 v87, 1.0, v66
	v_add_f32_e32 v89, 1.0, v67
	v_rcp_f32_e32 v64, v68
	v_rcp_f32_e32 v65, v69
	v_rcp_f32_e32 v66, v70
	v_rcp_f32_e32 v67, v71
	v_rcp_f32_e32 v68, v81
	v_rcp_f32_e32 v69, v86
	v_rcp_f32_e32 v70, v87
	v_rcp_f32_e32 v71, v89
	v_pk_mul_f32 v[64:65], v[88:89], v[64:65] op_sel_hi:[0,1]
	v_pk_mul_f32 v[66:67], v[88:89], v[66:67] op_sel_hi:[0,1]
	v_pk_mul_f32 v[68:69], v[88:89], v[68:69] op_sel_hi:[0,1]
	v_pk_mul_f32 v[70:71], v[88:89], v[70:71] op_sel_hi:[0,1]
	v_pk_mul_f32 v[66:67], v[78:79], v[66:67]
	v_pk_mul_f32 v[64:65], v[76:77], v[64:65]
	v_pk_mul_f32 v[70:71], v[74:75], v[70:71]
	v_pk_mul_f32 v[68:69], v[72:73], v[68:69]
	v_cvt_pk_bf16_f32 v64, v64, v65
	v_cvt_pk_bf16_f32 v65, v66, v67
	s_nop 0
	v_cvt_pk_bf16_f32 v66, v68, v69
	v_cvt_pk_bf16_f32 v67, v70, v71
	global_store_dwordx4 v[82:83], v[64:67], off
	s_nop 1
	s_nop 0
	v_add_u32_e32 v64, 0x90, v132
	v_mad_i64_i32 v[66:67], s[26:27], v80, s46, v[120:121]
	v_lshl_add_u64 v[66:67], v[66:67], 0, v[122:123]
	s_waitcnt vmcnt(7)
	v_fmamk_f32 v65, v228, 0x3a000000, v152
	v_rsq_f32_e32 v71, v65
	v_ashrrev_i32_e32 v65, 31, v64
	v_lshl_add_u64 v[68:69], v[64:65], 2, s[8:9]
	v_mul_f32_e32 v70, 0xbfb8aa3b, v71
	v_pk_mul_f32 v[54:55], v[54:55], v[70:71] op_sel_hi:[1,0]
	v_pk_mul_f32 v[52:53], v[52:53], v[70:71] op_sel_hi:[1,0]
	v_pk_mul_f32 v[50:51], v[50:51], v[70:71] op_sel_hi:[1,0]
	v_pk_mul_f32 v[48:49], v[48:49], v[70:71] op_sel_hi:[1,0]
	v_exp_f32_e32 v52, v52
	v_exp_f32_e32 v53, v53
	v_exp_f32_e32 v54, v54
	v_exp_f32_e32 v55, v55
	v_exp_f32_e32 v48, v48
	v_exp_f32_e32 v49, v49
	v_exp_f32_e32 v50, v50
	v_exp_f32_e32 v51, v51
	v_add_f32_e32 v52, 1.0, v52
	v_add_f32_e32 v53, 1.0, v53
	v_add_f32_e32 v54, 1.0, v54
	v_add_f32_e32 v55, 1.0, v55
	v_mul_f32_e32 v72, v71, v71
	v_add_f32_e32 v65, 1.0, v48
	v_add_f32_e32 v70, 1.0, v49
	v_add_f32_e32 v71, 1.0, v50
	v_add_f32_e32 v73, 1.0, v51
	v_rcp_f32_e32 v48, v52
	v_rcp_f32_e32 v49, v53
	v_rcp_f32_e32 v50, v54
	v_rcp_f32_e32 v51, v55
	v_rcp_f32_e32 v52, v65
	v_rcp_f32_e32 v53, v70
	v_rcp_f32_e32 v54, v71
	v_rcp_f32_e32 v55, v73
	v_pk_mul_f32 v[48:49], v[72:73], v[48:49] op_sel_hi:[0,1]
	v_pk_mul_f32 v[50:51], v[72:73], v[50:51] op_sel_hi:[0,1]
	v_pk_mul_f32 v[52:53], v[72:73], v[52:53] op_sel_hi:[0,1]
	v_pk_mul_f32 v[54:55], v[72:73], v[54:55] op_sel_hi:[0,1]
	v_pk_mul_f32 v[50:51], v[62:63], v[50:51]
	v_pk_mul_f32 v[48:49], v[60:61], v[48:49]
	v_pk_mul_f32 v[54:55], v[58:59], v[54:55]
	v_pk_mul_f32 v[52:53], v[56:57], v[52:53]
	v_cvt_pk_bf16_f32 v48, v48, v49
	v_cvt_pk_bf16_f32 v49, v50, v51
	s_nop 0
	v_cvt_pk_bf16_f32 v50, v52, v53
	v_cvt_pk_bf16_f32 v51, v54, v55
	global_store_dwordx4 v[66:67], v[48:51], off
	s_nop 1
	s_nop 0
	v_add_u32_e32 v48, 0xa0, v132
	v_mad_i64_i32 v[50:51], s[26:27], v64, s46, v[120:121]
	v_lshl_add_u64 v[50:51], v[50:51], 0, v[122:123]
	s_waitcnt vmcnt(7)
; __device__ __forceinline__ u32x4 pack8(f32x4 v0, f32x4 v1) { u32x4 w; w.x = cvt_pk_bf16(v0[0], v0[1]); w.y = cvt_pk_bf16(v0[2], v0[3]); w.z = cvt_pk_bf16(v1[0], v1[1]); w.w = cvt_pk_bf16(v1[2], v1[3]); return w; }
;     __device__ __forceinline__ void operator()(EPI_ARGS) const {
;         const int col0 = u.pn * 128 + wc * 32 + 8 * fq;
; #pragma unroll
;         for (int ai = 0; ai < 2; ++ai)
; #pragma unroll
;             for (int m = 0; m < 4; ++m) { const int row = EPI_ROW(ai, m); const float rs = __builtin_amdgcn_rsqf(rsq[row] * (1.f / DM) + RMS_EPS); f32x4 v0, v1;
;                 const float c1 = -1.4426950408889634f * rs, rs2 = rs * rs;
;                 { const f32x4 g = acc[ai][0][m][0], u = acc[ai][1][m][0]; f32x4 t = g * c1, r;
; #pragma unroll
;                   for (int e = 0; e < 4; ++e) t[e] = __builtin_amdgcn_exp2f(t[e]);
;                   t = t + 1.f;
; #pragma unroll
;                   for (int e = 0; e < 4; ++e) r[e] = __builtin_amdgcn_rcpf(t[e]);
;                   v0 = (g * u) * (r * rs2); }
;                 { const f32x4 g = acc[ai][0][m][1], u = acc[ai][1][m][1]; f32x4 t = g * c1, r;
; #pragma unroll
;                   for (int e = 0; e < 4; ++e) t[e] = __builtin_amdgcn_exp2f(t[e]);
;                   t = t + 1.f;
; #pragma unroll
;                   for (int e = 0; e < 4; ++e) r[e] = __builtin_amdgcn_rcpf(t[e]);
;                   v1 = (g * u) * (r * rs2); }
;                 *(u32x4*)(H + (size_t)row * DFF + col0) = pack8(v0, v1);
;                 if (m & 1) asm volatile("" ::: "memory"); }
;     }
	v_fmamk_f32 v49, v229, 0x3a000000, v152
	v_rsq_f32_e32 v55, v49
	v_ashrrev_i32_e32 v49, 31, v48
	v_lshl_add_u64 v[52:53], v[48:49], 2, s[8:9]
	v_mul_f32_e32 v54, 0xbfb8aa3b, v55
	v_pk_mul_f32 v[38:39], v[38:39], v[54:55] op_sel_hi:[1,0]
	v_pk_mul_f32 v[36:37], v[36:37], v[54:55] op_sel_hi:[1,0]
	v_pk_mul_f32 v[34:35], v[34:35], v[54:55] op_sel_hi:[1,0]
	v_pk_mul_f32 v[32:33], v[32:33], v[54:55] op_sel_hi:[1,0]
	v_exp_f32_e32 v36, v36
	v_exp_f32_e32 v37, v37
	v_exp_f32_e32 v38, v38
	v_exp_f32_e32 v39, v39
	v_exp_f32_e32 v32, v32
	v_exp_f32_e32 v33, v33
	v_exp_f32_e32 v34, v34
	v_exp_f32_e32 v35, v35
	v_add_f32_e32 v36, 1.0, v36
	v_add_f32_e32 v37, 1.0, v37
	v_add_f32_e32 v38, 1.0, v38
	v_add_f32_e32 v39, 1.0, v39
	v_mul_f32_e32 v56, v55, v55
	v_add_f32_e32 v49, 1.0, v32
	v_add_f32_e32 v54, 1.0, v33
	v_add_f32_e32 v55, 1.0, v34
	v_add_f32_e32 v57, 1.0, v35
	v_rcp_f32_e32 v32, v36
	v_rcp_f32_e32 v33, v37
	v_rcp_f32_e32 v34, v38
	v_rcp_f32_e32 v35, v39
	v_rcp_f32_e32 v36, v49
	v_rcp_f32_e32 v37, v54
	v_rcp_f32_e32 v38, v55
	v_rcp_f32_e32 v39, v57
	v_pk_mul_f32 v[32:33], v[56:57], v[32:33] op_sel_hi:[0,1]
	v_pk_mul_f32 v[34:35], v[56:57], v[34:35] op_sel_hi:[0,1]
	v_pk_mul_f32 v[36:37], v[56:57], v[36:37] op_sel_hi:[0,1]
	v_pk_mul_f32 v[38:39], v[56:57], v[38:39] op_sel_hi:[0,1]
	v_pk_mul_f32 v[34:35], v[46:47], v[34:35]
	v_pk_mul_f32 v[32:33], v[44:45], v[32:33]
	v_pk_mul_f32 v[38:39], v[42:43], v[38:39]
	v_pk_mul_f32 v[36:37], v[40:41], v[36:37]
	v_cvt_pk_bf16_f32 v32, v32, v33
	v_cvt_pk_bf16_f32 v33, v34, v35
	s_nop 0
	v_cvt_pk_bf16_f32 v34, v36, v37
	v_cvt_pk_bf16_f32 v35, v38, v39
	global_store_dwordx4 v[50:51], v[32:35], off
	s_nop 1
	s_nop 0
	v_add_u32_e32 v32, 0xb0, v132
	v_mad_i64_i32 v[34:35], s[26:27], v48, s46, v[120:121]
	v_lshl_add_u64 v[34:35], v[34:35], 0, v[122:123]
	s_waitcnt vmcnt(7)
	v_fmamk_f32 v33, v230, 0x3a000000, v152
	v_rsq_f32_e32 v39, v33
	v_ashrrev_i32_e32 v33, 31, v32
	v_lshl_add_u64 v[36:37], v[32:33], 2, s[8:9]
	v_mul_f32_e32 v38, 0xbfb8aa3b, v39
	v_pk_mul_f32 v[22:23], v[22:23], v[38:39] op_sel_hi:[1,0]
	v_pk_mul_f32 v[20:21], v[20:21], v[38:39] op_sel_hi:[1,0]
	v_pk_mul_f32 v[18:19], v[18:19], v[38:39] op_sel_hi:[1,0]
	v_pk_mul_f32 v[16:17], v[16:17], v[38:39] op_sel_hi:[1,0]
	v_exp_f32_e32 v20, v20
	v_exp_f32_e32 v21, v21
	v_exp_f32_e32 v22, v22
	v_exp_f32_e32 v23, v23
	v_exp_f32_e32 v16, v16
	v_exp_f32_e32 v17, v17
	v_exp_f32_e32 v18, v18
	v_exp_f32_e32 v19, v19
	v_add_f32_e32 v20, 1.0, v20
	v_add_f32_e32 v21, 1.0, v21
	v_add_f32_e32 v22, 1.0, v22
	v_add_f32_e32 v23, 1.0, v23
	v_mul_f32_e32 v40, v39, v39
	v_add_f32_e32 v33, 1.0, v16
	v_add_f32_e32 v38, 1.0, v17
	v_add_f32_e32 v39, 1.0, v18
	v_add_f32_e32 v41, 1.0, v19
	v_rcp_f32_e32 v16, v20
	v_rcp_f32_e32 v17, v21
	v_rcp_f32_e32 v18, v22
	v_rcp_f32_e32 v19, v23
	v_rcp_f32_e32 v20, v33
	v_rcp_f32_e32 v21, v38
	v_rcp_f32_e32 v22, v39
	v_rcp_f32_e32 v23, v41
	v_pk_mul_f32 v[16:17], v[40:41], v[16:17] op_sel_hi:[0,1]
	v_pk_mul_f32 v[18:19], v[40:41], v[18:19] op_sel_hi:[0,1]
	v_pk_mul_f32 v[20:21], v[40:41], v[20:21] op_sel_hi:[0,1]
	v_pk_mul_f32 v[22:23], v[40:41], v[22:23] op_sel_hi:[0,1]
	v_pk_mul_f32 v[18:19], v[30:31], v[18:19]
	v_pk_mul_f32 v[16:17], v[28:29], v[16:17]
	v_pk_mul_f32 v[22:23], v[26:27], v[22:23]
	v_pk_mul_f32 v[20:21], v[24:25], v[20:21]
	v_cvt_pk_bf16_f32 v16, v16, v17
	v_cvt_pk_bf16_f32 v17, v18, v19
	s_nop 0
	v_cvt_pk_bf16_f32 v18, v20, v21
	v_cvt_pk_bf16_f32 v19, v22, v23
	global_store_dwordx4 v[34:35], v[16:19], off
	s_nop 1
	s_waitcnt vmcnt(7)
	v_fmamk_f32 v16, v231, 0x3a000000, v152
	v_rsq_f32_e32 v19, v16
	v_mad_i64_i32 v[16:17], s[26:27], v32, s46, v[120:121]
	v_lshl_add_u64 v[16:17], v[16:17], 0, v[122:123]
	v_mul_f32_e32 v18, 0xbfb8aa3b, v19
	v_pk_mul_f32 v[10:11], v[10:11], v[18:19] op_sel_hi:[1,0]
	v_pk_mul_f32 v[8:9], v[8:9], v[18:19] op_sel_hi:[1,0]
	v_pk_mul_f32 v[6:7], v[6:7], v[18:19] op_sel_hi:[1,0]
	v_pk_mul_f32 v[4:5], v[4:5], v[18:19] op_sel_hi:[1,0]
	v_exp_f32_e32 v8, v8
	v_exp_f32_e32 v9, v9
	v_exp_f32_e32 v10, v10
	v_exp_f32_e32 v11, v11
	v_exp_f32_e32 v4, v4
	v_exp_f32_e32 v5, v5
	v_exp_f32_e32 v6, v6
	v_exp_f32_e32 v7, v7
	v_mul_f32_e32 v20, v19, v19
	v_add_f32_e32 v8, 1.0, v8
	v_add_f32_e32 v9, 1.0, v9
	v_add_f32_e32 v10, 1.0, v10
	v_add_f32_e32 v11, 1.0, v11
	v_add_f32_e32 v18, 1.0, v4
	v_add_f32_e32 v19, 1.0, v5
	v_add_f32_e32 v21, 1.0, v6
	v_add_f32_e32 v22, 1.0, v7
	v_rcp_f32_e32 v4, v8
	v_rcp_f32_e32 v5, v9
	v_rcp_f32_e32 v6, v10
	v_rcp_f32_e32 v7, v11
	v_rcp_f32_e32 v8, v18
	v_rcp_f32_e32 v9, v19
	v_rcp_f32_e32 v10, v21
	v_rcp_f32_e32 v11, v22
	v_pk_mul_f32 v[4:5], v[20:21], v[4:5] op_sel_hi:[0,1]
	v_pk_mul_f32 v[8:9], v[20:21], v[8:9] op_sel_hi:[0,1]
	v_pk_mul_f32 v[6:7], v[20:21], v[6:7] op_sel_hi:[0,1]
	v_pk_mul_f32 v[10:11], v[20:21], v[10:11] op_sel_hi:[0,1]
	v_pk_mul_f32 v[10:11], v[2:3], v[10:11]
	v_pk_mul_f32 v[2:3], v[0:1], v[8:9]
	v_pk_mul_f32 v[6:7], v[14:15], v[6:7]
	v_pk_mul_f32 v[4:5], v[12:13], v[4:5]
	s_nop 0
	v_cvt_pk_bf16_f32 v0, v4, v5
	v_cvt_pk_bf16_f32 v1, v6, v7
	v_cvt_pk_bf16_f32 v2, v2, v3
	v_cvt_pk_bf16_f32 v3, v10, v11
	global_store_dwordx4 v[16:17], v[0:3], off
	s_cbranch_vccnz .LBB0_892
	s_andn2_b64 vcc, exec, s[6:7]
	s_cbranch_vccnz .LBB0_891
	s_barrier
	s_branch .LBB0_891
